# pool pass de-serialised: window-init loads issued together (exec-masked) and the row loop software-pipelined one row deep with vmcnt(1) (store acks not waited for)
# speedup vs baseline: 1.0136x; 1.0136x over previous
; __device__ __forceinline__ u32x4 zero4() { unsigned z = 0u; asm volatile("" : "+v"(z)); return (u32x4){z, z, z, z}; }
; __device__ __forceinline__ void unpack8(const u32x4& w, float (&v)[8]) { v[0] = bf_lo(w.x); v[1] = bf_hi(w.x); v[2] = bf_lo(w.y); v[3] = bf_hi(w.y); v[4] = bf_lo(w.z); v[5] = bf_hi(w.z); v[6] = bf_lo(w.w); v[7] = bf_hi(w.w); }
; __device__ __forceinline__ void phase_pool(const Args& a, int l, int vcu, int NGW, int wv) {
;     ...
;     const int g = lane >> 4, w = 2 << g;
;     constexpr int CR = 17, CPB = (LP + CR - 1) / CR;
;     for (int ch = gw; ch < BATCH * CPB; ch += NGW) {
;         const int bb = ch / CPB, p0 = (ch - bb * CPB) * CR, r0 = bb * LP + p0, nrows = (LP - p0 < CR) ? LP - p0 : CR;
;         if (p0 + CR <= PADF) {
;             const u32x4 zz = zero4();
;             for (int i = 0; i < nrows; ++i) *(u32x4*)(proj + (size_t)(r0 + i) * PW + C_P1Y + 8 * lane) = zz;
;             continue; }
;         float S[8];
; #pragma unroll
;         for (int i = 0; i < 8; ++i) S[i] = 0.f;
;         for (int j = 1; j < w; ++j) { const u32x4 uw = *(const u32x4*)(proj + (size_t)(r0 - j) * PW + C_U + 8 * lane); float u[8]; unpack8(uw, u);
; #pragma unroll
;             for (int i = 0; i < 8; ++i) S[i] += u[i]; }
.LBB0_221:
	s_movk_i32 s14, 0xdc00
	s_mov_b32 s15, -1
	s_mov_b64 s[40:41], exec
	v_cmp_le_u32_e64 s[34:35], 2, v50
	v_cmp_le_u32_e64 s[36:37], 4, v50
	v_cmp_le_u32_e64 s[38:39], 8, v50
	global_load_dwordx4 v[64:67], v[10:11], off
	v_lshl_add_u64 v[10:11], v[10:11], 0, s[14:15]
	s_mov_b64 exec, s[34:35]
	global_load_dwordx4 v[68:71], v[10:11], off
	v_lshl_add_u64 v[10:11], v[10:11], 0, s[14:15]
	global_load_dwordx4 v[72:75], v[10:11], off
	v_lshl_add_u64 v[10:11], v[10:11], 0, s[14:15]
	s_mov_b64 exec, s[36:37]
	global_load_dwordx4 v[76:79], v[10:11], off
	v_lshl_add_u64 v[10:11], v[10:11], 0, s[14:15]
	global_load_dwordx4 v[80:83], v[10:11], off
	v_lshl_add_u64 v[10:11], v[10:11], 0, s[14:15]
	global_load_dwordx4 v[84:87], v[10:11], off
	v_lshl_add_u64 v[10:11], v[10:11], 0, s[14:15]
	global_load_dwordx4 v[88:91], v[10:11], off
	v_lshl_add_u64 v[10:11], v[10:11], 0, s[14:15]
	s_mov_b64 exec, s[38:39]
	global_load_dwordx4 v[92:95], v[10:11], off
	v_lshl_add_u64 v[10:11], v[10:11], 0, s[14:15]
	global_load_dwordx4 v[96:99], v[10:11], off
	v_lshl_add_u64 v[10:11], v[10:11], 0, s[14:15]
	global_load_dwordx4 v[100:103], v[10:11], off
	v_lshl_add_u64 v[10:11], v[10:11], 0, s[14:15]
	global_load_dwordx4 v[104:107], v[10:11], off
	v_lshl_add_u64 v[10:11], v[10:11], 0, s[14:15]
	global_load_dwordx4 v[108:111], v[10:11], off
	v_lshl_add_u64 v[10:11], v[10:11], 0, s[14:15]
	global_load_dwordx4 v[112:115], v[10:11], off
	v_lshl_add_u64 v[10:11], v[10:11], 0, s[14:15]
	global_load_dwordx4 v[116:119], v[10:11], off
	v_lshl_add_u64 v[10:11], v[10:11], 0, s[14:15]
	global_load_dwordx4 v[120:123], v[10:11], off
	s_mov_b64 exec, s[40:41]
	s_waitcnt vmcnt(14)
	v_lshlrev_b32_e32 v12, 16, v64
	v_and_b32_e32 v13, 0xffff0000, v64
	v_lshlrev_b32_e32 v24, 16, v65
	v_and_b32_e32 v25, 0xffff0000, v65
	v_lshlrev_b32_e32 v34, 16, v66
	v_and_b32_e32 v35, 0xffff0000, v66
	v_lshlrev_b32_e32 v36, 16, v67
	v_and_b32_e32 v37, 0xffff0000, v67
	v_pk_add_f32 v[28:29], v[28:29], v[12:13]
	v_pk_add_f32 v[30:31], v[30:31], v[24:25]
	v_pk_add_f32 v[32:33], v[32:33], v[34:35]
	v_pk_add_f32 v[26:27], v[26:27], v[36:37]
	s_mov_b64 exec, s[34:35]
	s_waitcnt vmcnt(13)
	v_lshlrev_b32_e32 v12, 16, v68
	v_and_b32_e32 v13, 0xffff0000, v68
	v_lshlrev_b32_e32 v24, 16, v69
	v_and_b32_e32 v25, 0xffff0000, v69
	v_lshlrev_b32_e32 v34, 16, v70
	v_and_b32_e32 v35, 0xffff0000, v70
	v_lshlrev_b32_e32 v36, 16, v71
	v_and_b32_e32 v37, 0xffff0000, v71
	v_pk_add_f32 v[28:29], v[28:29], v[12:13]
	v_pk_add_f32 v[30:31], v[30:31], v[24:25]
	v_pk_add_f32 v[32:33], v[32:33], v[34:35]
	v_pk_add_f32 v[26:27], v[26:27], v[36:37]
	s_waitcnt vmcnt(12)
	v_lshlrev_b32_e32 v12, 16, v72
	v_and_b32_e32 v13, 0xffff0000, v72
	v_lshlrev_b32_e32 v24, 16, v73
	v_and_b32_e32 v25, 0xffff0000, v73
	v_lshlrev_b32_e32 v34, 16, v74
	v_and_b32_e32 v35, 0xffff0000, v74
	v_lshlrev_b32_e32 v36, 16, v75
	v_and_b32_e32 v37, 0xffff0000, v75
	v_pk_add_f32 v[28:29], v[28:29], v[12:13]
	v_pk_add_f32 v[30:31], v[30:31], v[24:25]
	v_pk_add_f32 v[32:33], v[32:33], v[34:35]
	v_pk_add_f32 v[26:27], v[26:27], v[36:37]
	s_mov_b64 exec, s[36:37]
	s_waitcnt vmcnt(11)
	v_lshlrev_b32_e32 v12, 16, v76
	v_and_b32_e32 v13, 0xffff0000, v76
	v_lshlrev_b32_e32 v24, 16, v77
	v_and_b32_e32 v25, 0xffff0000, v77
	v_lshlrev_b32_e32 v34, 16, v78
	v_and_b32_e32 v35, 0xffff0000, v78
	v_lshlrev_b32_e32 v36, 16, v79
	v_and_b32_e32 v37, 0xffff0000, v79
	v_pk_add_f32 v[28:29], v[28:29], v[12:13]
	v_pk_add_f32 v[30:31], v[30:31], v[24:25]
	v_pk_add_f32 v[32:33], v[32:33], v[34:35]
	v_pk_add_f32 v[26:27], v[26:27], v[36:37]
	s_waitcnt vmcnt(10)
	v_lshlrev_b32_e32 v12, 16, v80
	v_and_b32_e32 v13, 0xffff0000, v80
	v_lshlrev_b32_e32 v24, 16, v81
	v_and_b32_e32 v25, 0xffff0000, v81
	v_lshlrev_b32_e32 v34, 16, v82
	v_and_b32_e32 v35, 0xffff0000, v82
	v_lshlrev_b32_e32 v36, 16, v83
	v_and_b32_e32 v37, 0xffff0000, v83
	v_pk_add_f32 v[28:29], v[28:29], v[12:13]
	v_pk_add_f32 v[30:31], v[30:31], v[24:25]
	v_pk_add_f32 v[32:33], v[32:33], v[34:35]
	v_pk_add_f32 v[26:27], v[26:27], v[36:37]
	s_waitcnt vmcnt(9)
	v_lshlrev_b32_e32 v12, 16, v84
	v_and_b32_e32 v13, 0xffff0000, v84
	v_lshlrev_b32_e32 v24, 16, v85
	v_and_b32_e32 v25, 0xffff0000, v85
	v_lshlrev_b32_e32 v34, 16, v86
	v_and_b32_e32 v35, 0xffff0000, v86
	v_lshlrev_b32_e32 v36, 16, v87
	v_and_b32_e32 v37, 0xffff0000, v87
	v_pk_add_f32 v[28:29], v[28:29], v[12:13]
	v_pk_add_f32 v[30:31], v[30:31], v[24:25]
	v_pk_add_f32 v[32:33], v[32:33], v[34:35]
	v_pk_add_f32 v[26:27], v[26:27], v[36:37]
	s_waitcnt vmcnt(8)
	v_lshlrev_b32_e32 v12, 16, v88
	v_and_b32_e32 v13, 0xffff0000, v88
	v_lshlrev_b32_e32 v24, 16, v89
	v_and_b32_e32 v25, 0xffff0000, v89
	v_lshlrev_b32_e32 v34, 16, v90
	v_and_b32_e32 v35, 0xffff0000, v90
	v_lshlrev_b32_e32 v36, 16, v91
	v_and_b32_e32 v37, 0xffff0000, v91
	v_pk_add_f32 v[28:29], v[28:29], v[12:13]
	v_pk_add_f32 v[30:31], v[30:31], v[24:25]
	v_pk_add_f32 v[32:33], v[32:33], v[34:35]
	v_pk_add_f32 v[26:27], v[26:27], v[36:37]
	s_mov_b64 exec, s[38:39]
	s_waitcnt vmcnt(7)
	v_lshlrev_b32_e32 v12, 16, v92
	v_and_b32_e32 v13, 0xffff0000, v92
	v_lshlrev_b32_e32 v24, 16, v93
	v_and_b32_e32 v25, 0xffff0000, v93
	v_lshlrev_b32_e32 v34, 16, v94
	v_and_b32_e32 v35, 0xffff0000, v94
	v_lshlrev_b32_e32 v36, 16, v95
	v_and_b32_e32 v37, 0xffff0000, v95
	v_pk_add_f32 v[28:29], v[28:29], v[12:13]
	v_pk_add_f32 v[30:31], v[30:31], v[24:25]
	v_pk_add_f32 v[32:33], v[32:33], v[34:35]
	v_pk_add_f32 v[26:27], v[26:27], v[36:37]
	s_waitcnt vmcnt(6)
; __device__ __forceinline__ u32x4 pack8(const f32x4& a, const f32x4& b) { u32x4 w; w.x = cvt_pk_bf16(a[0], a[1]); w.y = cvt_pk_bf16(a[2], a[3]); w.z = cvt_pk_bf16(b[0], b[1]); w.w = cvt_pk_bf16(b[2], b[3]); return w; }
; __device__ __forceinline__ void unpack8(const u32x4& w, float (&v)[8]) { v[0] = bf_lo(w.x); v[1] = bf_hi(w.x); v[2] = bf_lo(w.y); v[3] = bf_hi(w.y); v[4] = bf_lo(w.z); v[5] = bf_hi(w.z); v[6] = bf_lo(w.w); v[7] = bf_hi(w.w); }
; __device__ __forceinline__ void phase_pool(const Args& a, int l, int vcu, int NGW, int wv) {
;     ...
;         for (int j = 1; j < w; ++j) { const u32x4 uw = *(const u32x4*)(proj + (size_t)(r0 - j) * PW + C_U + 8 * lane); float u[8]; unpack8(uw, u);
; #pragma unroll
;             for (int i = 0; i < 8; ++i) S[i] += u[i]; }
; #pragma unroll 2
;         for (int i = 0; i < nrows; ++i) {
;             const int m = r0 + i, t = p0 + i - PADF;
;             bf16_t* prow = proj + (size_t)m * PW;
;             const u32x4 uw = *(const u32x4*)(prow + C_U + 8 * lane); float u[8]; unpack8(uw, u);
;             const u32x4 zw = *(const u32x4*)(prow + C_Z + 8 * lane); float z[8]; unpack8(zw, z);
;             const u32x4 ow = *(const u32x4*)(proj + (size_t)(m - (w - 1)) * PW + C_U + 8 * lane); float o[8]; unpack8(ow, o);
;     ...
;             *(u32x4*)(prow + C_P1Y + 8 * lane) = pack8(r0v, r1v);
; #pragma unroll
;             for (int k = 0; k < 8; ++k) S[k] -= o[k];
	v_lshlrev_b32_e32 v12, 16, v96
	v_and_b32_e32 v13, 0xffff0000, v96
	v_lshlrev_b32_e32 v24, 16, v97
	v_and_b32_e32 v25, 0xffff0000, v97
	v_lshlrev_b32_e32 v34, 16, v98
	v_and_b32_e32 v35, 0xffff0000, v98
	v_lshlrev_b32_e32 v36, 16, v99
	v_and_b32_e32 v37, 0xffff0000, v99
	v_pk_add_f32 v[28:29], v[28:29], v[12:13]
	v_pk_add_f32 v[30:31], v[30:31], v[24:25]
	v_pk_add_f32 v[32:33], v[32:33], v[34:35]
	v_pk_add_f32 v[26:27], v[26:27], v[36:37]
	s_waitcnt vmcnt(5)
	v_lshlrev_b32_e32 v12, 16, v100
	v_and_b32_e32 v13, 0xffff0000, v100
	v_lshlrev_b32_e32 v24, 16, v101
	v_and_b32_e32 v25, 0xffff0000, v101
	v_lshlrev_b32_e32 v34, 16, v102
	v_and_b32_e32 v35, 0xffff0000, v102
	v_lshlrev_b32_e32 v36, 16, v103
	v_and_b32_e32 v37, 0xffff0000, v103
	v_pk_add_f32 v[28:29], v[28:29], v[12:13]
	v_pk_add_f32 v[30:31], v[30:31], v[24:25]
	v_pk_add_f32 v[32:33], v[32:33], v[34:35]
	v_pk_add_f32 v[26:27], v[26:27], v[36:37]
	s_waitcnt vmcnt(4)
	v_lshlrev_b32_e32 v12, 16, v104
	v_and_b32_e32 v13, 0xffff0000, v104
	v_lshlrev_b32_e32 v24, 16, v105
	v_and_b32_e32 v25, 0xffff0000, v105
	v_lshlrev_b32_e32 v34, 16, v106
	v_and_b32_e32 v35, 0xffff0000, v106
	v_lshlrev_b32_e32 v36, 16, v107
	v_and_b32_e32 v37, 0xffff0000, v107
	v_pk_add_f32 v[28:29], v[28:29], v[12:13]
	v_pk_add_f32 v[30:31], v[30:31], v[24:25]
	v_pk_add_f32 v[32:33], v[32:33], v[34:35]
	v_pk_add_f32 v[26:27], v[26:27], v[36:37]
	s_waitcnt vmcnt(3)
	v_lshlrev_b32_e32 v12, 16, v108
	v_and_b32_e32 v13, 0xffff0000, v108
	v_lshlrev_b32_e32 v24, 16, v109
	v_and_b32_e32 v25, 0xffff0000, v109
	v_lshlrev_b32_e32 v34, 16, v110
	v_and_b32_e32 v35, 0xffff0000, v110
	v_lshlrev_b32_e32 v36, 16, v111
	v_and_b32_e32 v37, 0xffff0000, v111
	v_pk_add_f32 v[28:29], v[28:29], v[12:13]
	v_pk_add_f32 v[30:31], v[30:31], v[24:25]
	v_pk_add_f32 v[32:33], v[32:33], v[34:35]
	v_pk_add_f32 v[26:27], v[26:27], v[36:37]
	s_waitcnt vmcnt(2)
	v_lshlrev_b32_e32 v12, 16, v112
	v_and_b32_e32 v13, 0xffff0000, v112
	v_lshlrev_b32_e32 v24, 16, v113
	v_and_b32_e32 v25, 0xffff0000, v113
	v_lshlrev_b32_e32 v34, 16, v114
	v_and_b32_e32 v35, 0xffff0000, v114
	v_lshlrev_b32_e32 v36, 16, v115
	v_and_b32_e32 v37, 0xffff0000, v115
	v_pk_add_f32 v[28:29], v[28:29], v[12:13]
	v_pk_add_f32 v[30:31], v[30:31], v[24:25]
	v_pk_add_f32 v[32:33], v[32:33], v[34:35]
	v_pk_add_f32 v[26:27], v[26:27], v[36:37]
	s_waitcnt vmcnt(1)
	v_lshlrev_b32_e32 v12, 16, v116
	v_and_b32_e32 v13, 0xffff0000, v116
	v_lshlrev_b32_e32 v24, 16, v117
	v_and_b32_e32 v25, 0xffff0000, v117
	v_lshlrev_b32_e32 v34, 16, v118
	v_and_b32_e32 v35, 0xffff0000, v118
	v_lshlrev_b32_e32 v36, 16, v119
	v_and_b32_e32 v37, 0xffff0000, v119
	v_pk_add_f32 v[28:29], v[28:29], v[12:13]
	v_pk_add_f32 v[30:31], v[30:31], v[24:25]
	v_pk_add_f32 v[32:33], v[32:33], v[34:35]
	v_pk_add_f32 v[26:27], v[26:27], v[36:37]
	s_waitcnt vmcnt(0)
	v_lshlrev_b32_e32 v12, 16, v120
	v_and_b32_e32 v13, 0xffff0000, v120
	v_lshlrev_b32_e32 v24, 16, v121
	v_and_b32_e32 v25, 0xffff0000, v121
	v_lshlrev_b32_e32 v34, 16, v122
	v_and_b32_e32 v35, 0xffff0000, v122
	v_lshlrev_b32_e32 v36, 16, v123
	v_and_b32_e32 v37, 0xffff0000, v123
	v_pk_add_f32 v[28:29], v[28:29], v[12:13]
	v_pk_add_f32 v[30:31], v[30:31], v[24:25]
	v_pk_add_f32 v[32:33], v[32:33], v[34:35]
	v_pk_add_f32 v[26:27], v[26:27], v[36:37]
	s_mov_b64 exec, s[40:41]
	s_cmpk_gt_u32 s12, 0x1e9
	s_cbranch_scc1 .LBB0_227
	s_mul_i32 s0, s5, 0x208a
	s_add_i32 s1, s3, s0
	v_med3_i32 v5, s1, 1, 17
	s_sub_i32 s0, s4, s0
	v_subrev_u32_e32 v9, s6, v0
	s_mov_b32 s1, 0
	s_nop 0
	v_readfirstlane_b32 s14, v5
	s_add_i32 s12, s7, s1
	v_mad_i64_i32 v[76:77], s[44:45], s12, v233, v[14:15]
	global_load_dwordx4 v[64:67], v[76:77], off
	v_add_u32_e32 v78, s1, v9
	v_mad_i64_i32 v[78:79], s[44:45], v78, s29, v[14:15]
	global_load_dwordx4 v[68:71], v[78:79], off
	global_load_dwordx4 v[72:75], v[76:77], off offset:1024
	s_waitcnt vmcnt(0)
	s_branch .LBB0_225
.LBB0_224:
	s_add_i32 s1, s1, 1
	v_lshlrev_b32_e32 v34, 16, v10
	v_and_b32_e32 v35, 0xffff0000, v10
	v_lshlrev_b32_e32 v36, 16, v11
	v_and_b32_e32 v37, 0xffff0000, v11
	v_lshlrev_b32_e32 v44, 16, v12
	v_and_b32_e32 v45, 0xffff0000, v12
	v_lshlrev_b32_e32 v48, 16, v13
	v_and_b32_e32 v49, 0xffff0000, v13
	v_cmp_ne_u32_e32 vcc, s1, v5
	v_pk_add_f32 v[28:29], v[28:29], v[34:35] neg_lo:[0,1] neg_hi:[0,1]
	v_pk_add_f32 v[30:31], v[30:31], v[36:37] neg_lo:[0,1] neg_hi:[0,1]
	v_pk_add_f32 v[32:33], v[32:33], v[44:45] neg_lo:[0,1] neg_hi:[0,1]
	s_and_b64 vcc, exec, vcc
	v_pk_add_f32 v[26:27], v[26:27], v[48:49] neg_lo:[0,1] neg_hi:[0,1]
	v_cvt_pk_bf16_f32 v10, v38, v39
	v_cvt_pk_bf16_f32 v11, v40, v41
	v_cvt_pk_bf16_f32 v12, v42, v43
	v_cvt_pk_bf16_f32 v13, v46, v47
	global_store_dwordx4 v[24:25], v[10:13], off offset:1024
	s_cbranch_vccz .LBB0_227
	s_waitcnt vmcnt(1)
; __device__ __forceinline__ float siluf_(float z) { return z * sigmoidf_(z); }
; __device__ __forceinline__ u32x4 pack8(const f32x4& a, const f32x4& b) { u32x4 w; w.x = cvt_pk_bf16(a[0], a[1]); w.y = cvt_pk_bf16(a[2], a[3]); w.z = cvt_pk_bf16(b[0], b[1]); w.w = cvt_pk_bf16(b[2], b[3]); return w; }
; __device__ __forceinline__ void unpack8(const u32x4& w, float (&v)[8]) { v[0] = bf_lo(w.x); v[1] = bf_hi(w.x); v[2] = bf_lo(w.y); v[3] = bf_hi(w.y); v[4] = bf_lo(w.z); v[5] = bf_hi(w.z); v[6] = bf_lo(w.w); v[7] = bf_hi(w.w); }
; __device__ __forceinline__ void phase_pool(const Args& a, int l, int vcu, int NGW, int wv) {
;     ...
;         for (int i = 0; i < nrows; ++i) {
;             const int m = r0 + i, t = p0 + i - PADF;
;             bf16_t* prow = proj + (size_t)m * PW;
;             const u32x4 uw = *(const u32x4*)(prow + C_U + 8 * lane); float u[8]; unpack8(uw, u);
;             const u32x4 zw = *(const u32x4*)(prow + C_Z + 8 * lane); float z[8]; unpack8(zw, z);
;             const u32x4 ow = *(const u32x4*)(proj + (size_t)(m - (w - 1)) * PW + C_U + 8 * lane); float o[8]; unpack8(ow, o);
; #pragma unroll
;             for (int k = 0; k < 8; ++k) S[k] += u[k];
;             f32x4 r0v = (f32x4){0.f, 0.f, 0.f, 0.f}, r1v = r0v;
;             if (t >= 0) { const int cnt = (t + 1 < w) ? (t + 1) : w; const float ic = 1.0f / (float)cnt;
; #pragma unroll
;                 for (int k = 0; k < 4; ++k) { r0v[k] = (S[k] * ic - u[k]) * sc0[k] * siluf_(z[k]); r1v[k] = (S[4 + k] * ic - u[4 + k]) * sc1[k] * siluf_(z[4 + k]); } }
;             *(u32x4*)(prow + C_P1Y + 8 * lane) = pack8(r0v, r1v);
; #pragma unroll
;             for (int k = 0; k < 8; ++k) S[k] -= o[k];
.LBB0_225:
	s_add_i32 s12, s7, s1
	v_mad_i64_i32 v[24:25], s[12:13], s12, v233, v[14:15]
	v_mov_b32_e32 v52, v64
	v_mov_b32_e32 v53, v65
	v_mov_b32_e32 v54, v66
	v_mov_b32_e32 v55, v67
	v_mov_b32_e32 v10, v68
	v_mov_b32_e32 v11, v69
	v_mov_b32_e32 v12, v70
	v_mov_b32_e32 v13, v71
	v_mov_b32_e32 v80, v72
	v_mov_b32_e32 v81, v73
	v_mov_b32_e32 v82, v74
	v_mov_b32_e32 v83, v75
	s_add_i32 s15, s1, 1
	s_cmp_ge_u32 s15, s14
	s_cbranch_scc1 .Lpool_nopf
	s_add_i32 s12, s7, s15
	v_mad_i64_i32 v[76:77], s[44:45], s12, v233, v[14:15]
	global_load_dwordx4 v[64:67], v[76:77], off
	v_add_u32_e32 v78, s15, v9
	v_mad_i64_i32 v[78:79], s[44:45], v78, s29, v[14:15]
	global_load_dwordx4 v[68:71], v[78:79], off
	global_load_dwordx4 v[72:75], v[76:77], off offset:1024
.Lpool_nopf:
	s_add_i32 s12, s0, s1
	v_mov_b32_e32 v38, 0
	v_mov_b32_e32 v39, 0
	v_mov_b32_e32 v40, 0
	v_mov_b32_e32 v41, 0
	v_mov_b32_e32 v42, 0
	v_mov_b32_e32 v43, 0
	v_mov_b32_e32 v46, 0
	s_cmpk_lt_i32 s12, 0x70
	v_mov_b32_e32 v47, 0
	v_lshlrev_b32_e32 v48, 16, v52
	v_and_b32_e32 v49, 0xffff0000, v52
	v_lshlrev_b32_e32 v36, 16, v53
	v_and_b32_e32 v37, 0xffff0000, v53
	v_lshlrev_b32_e32 v44, 16, v54
	v_and_b32_e32 v45, 0xffff0000, v54
	v_lshlrev_b32_e32 v34, 16, v55
	v_and_b32_e32 v35, 0xffff0000, v55
	v_pk_add_f32 v[28:29], v[28:29], v[48:49]
	v_pk_add_f32 v[30:31], v[30:31], v[36:37]
	v_pk_add_f32 v[32:33], v[32:33], v[44:45]
	v_pk_add_f32 v[26:27], v[26:27], v[34:35]
	s_cbranch_scc1 .LBB0_224
	v_mov_b32_e32 v38, v80
	v_mov_b32_e32 v39, v81
	v_mov_b32_e32 v40, v82
	v_mov_b32_e32 v41, v83
	s_addk_i32 s12, 0xff91
	v_min_i32_e32 v21, s12, v17
	v_cvt_f32_u32_e32 v21, v21
	v_div_scale_f32 v23, s[12:13], v21, v21, 1.0
	v_rcp_f32_e32 v42, v23
	v_div_scale_f32 v43, vcc, 1.0, v21, 1.0
	v_fma_f32 v46, -v23, v42, 1.0
	v_fmac_f32_e32 v42, v46, v42
	v_mul_f32_e32 v46, v43, v42
	v_fma_f32 v47, -v23, v46, v43
	v_fmac_f32_e32 v46, v47, v42
	v_fma_f32 v23, -v23, v46, v43
	v_div_fmas_f32 v23, v23, v42, v46
	v_div_fixup_f32 v42, v23, v21, 1.0
	v_pk_fma_f32 v[46:47], v[42:43], v[28:29], v[48:49] op_sel_hi:[0,1,1] neg_lo:[0,0,1] neg_hi:[0,0,1]
	v_fma_f32 v21, v42, v30, -v36
	v_fma_f32 v23, v42, v26, -v34
	v_fma_f32 v34, v42, v31, -v37
	v_fma_f32 v36, v42, v27, -v35
	v_pk_fma_f32 v[44:45], v[42:43], v[32:33], v[44:45] op_sel_hi:[0,1,1] neg_lo:[0,0,1] neg_hi:[0,0,1]
	v_pk_mul_f32 v[42:43], v[2:3], v[46:47]
	v_mul_f32_e32 v46, v4, v21
	v_mul_f32_e32 v48, v8, v23
	v_pk_mul_f32 v[44:45], v[6:7], v[44:45]
	v_and_b32_e32 v35, 0xffff0000, v39
	v_and_b32_e32 v37, 0xffff0000, v41
	v_lshlrev_b32_e32 v52, 16, v38
	v_and_b32_e32 v53, 0xffff0000, v38
	v_lshlrev_b32_e32 v47, 16, v39
	v_lshlrev_b32_e32 v49, 16, v41
	v_lshlrev_b32_e32 v38, 16, v40
	v_and_b32_e32 v39, 0xffff0000, v40
	v_mul_f32_e32 v21, 0xbfb8aa3b, v52
	v_mul_f32_e32 v23, 0xbfb8aa3b, v53
	v_mul_f32_e32 v55, 0xbfb8aa3b, v35
	v_mul_f32_e32 v56, 0xbfb8aa3b, v37
	v_mul_f32_e32 v40, 0xbfb8aa3b, v38
	v_mul_f32_e32 v41, 0xbfb8aa3b, v39
	v_mul_f32_e32 v51, 0xbfb8aa3b, v47
	v_mul_f32_e32 v54, 0xbfb8aa3b, v49
	v_exp_f32_e32 v21, v21
	v_exp_f32_e32 v23, v23
	v_exp_f32_e32 v55, v55
	v_exp_f32_e32 v56, v56
	v_exp_f32_e32 v40, v40
	v_exp_f32_e32 v41, v41
	v_exp_f32_e32 v51, v51
	v_exp_f32_e32 v54, v54
	v_add_f32_e32 v21, 1.0, v21
	v_add_f32_e32 v23, 1.0, v23
	v_add_f32_e32 v60, 1.0, v55
	v_add_f32_e32 v56, 1.0, v56
	v_add_f32_e32 v57, 1.0, v40
	v_add_f32_e32 v58, 1.0, v41
	v_add_f32_e32 v51, 1.0, v51
	v_add_f32_e32 v59, 1.0, v54
	v_rcp_f32_e32 v40, v21
	v_rcp_f32_e32 v41, v23
	v_rcp_f32_e32 v21, v60
	v_rcp_f32_e32 v23, v56
	v_rcp_f32_e32 v54, v57
	v_rcp_f32_e32 v55, v58
	v_rcp_f32_e32 v51, v51
	v_rcp_f32_e32 v57, v59
	v_pk_mul_f32 v[34:35], v[20:21], v[34:35]
	v_pk_mul_f32 v[36:37], v[22:23], v[36:37]
	v_pk_mul_f32 v[40:41], v[40:41], v[52:53]
	v_pk_mul_f32 v[52:53], v[54:55], v[38:39]
	v_mul_f32_e32 v54, v51, v47
	v_mul_f32_e32 v56, v57, v49
	v_mov_b32_e32 v47, v34
	v_mov_b32_e32 v55, v35
	v_mov_b32_e32 v49, v36
	v_mov_b32_e32 v57, v37
	v_pk_mul_f32 v[38:39], v[42:43], v[40:41]
	v_pk_mul_f32 v[42:43], v[44:45], v[52:53]
	v_pk_mul_f32 v[40:41], v[46:47], v[54:55]
	v_pk_mul_f32 v[46:47], v[48:49], v[56:57]
	s_branch .LBB0_224
.LBB0_227:
	s_waitcnt vmcnt(0)
	s_mov_b64 s[0:1], 0
